# gating mixer: as previous (v-tile pair loads + merged preamble) with the non-temporal hint removed from the 8 u-tile loads only, so the u lines stay in L2 for the next quarter while every other stream
# baseline (speedup 1.0000x reference)
; #define LAS __attribute__((address_space(3)))
; __device__ __forceinline__ unsigned pk2(float lo, float hi) { return f2bf(lo) | (f2bf(hi) << 16); }
; __device__ __forceinline__ float bflo(unsigned w) { return __uint_as_float(w << 16); }
; __device__ __forceinline__ float bfhi(unsigned w) { return __uint_as_float(w & 0xffff0000u); }
; __device__ __forceinline__ void sgu_item(LAS unsigned char* wl, const bf16* proj, bf16* ymix, const float* vstat, const float* sgu_g, const bf16* Wm, const float* sgu_b, int chunk, int h, int lane) {
;     ...
;         for (int i = 0; i < 8; ++i) { const int s = rsub + 16 * i; const f32x2 ms = st[s]; const v4u w = raw[i];
;             v2u lo, hi; lo.x = pk2((bflo(w.x) - ms.x) * ms.y * g0[0], (bfhi(w.x) - ms.x) * ms.y * g0[1]); lo.y = pk2((bflo(w.y) - ms.x) * ms.y * g0[2], (bfhi(w.y) - ms.x) * ms.y * g0[3]);
;             hi.x = pk2((bflo(w.z) - ms.x) * ms.y * g1[0], (bfhi(w.z) - ms.x) * ms.y * g1[1]); hi.y = pk2((bflo(w.w) - ms.x) * ms.y * g1[2], (bfhi(w.w) - ms.x) * ms.y * g1[3]);
;             *(LAS v2u*)(wl + s * VP2 + (4 * c16) * 2) = lo; *(LAS v2u*)(wl + s * VP2 + (16 + 4 * c16) * 2) = hi; }
.Lsgu_go:
	v_lshlrev_b32_e32 v117, 16, v119
	v_lshlrev_b32_e32 v116, 16, v118
	v_and_b32_e32 v119, 0xffff0000, v119
	v_and_b32_e32 v118, 0xffff0000, v118
	ds_read_b64 v[122:123], v218 offset:10240
	v_lshl_add_u64 v[178:179], v[178:179], 0, s[88:89]
	s_waitcnt lgkmcnt(0)
	v_pk_add_f32 v[116:117], v[116:117], v[122:123] op_sel_hi:[1,0] neg_lo:[0,1] neg_hi:[0,1]
	s_nop 0
	v_pk_mul_f32 v[124:125], v[122:123], v[116:117] op_sel:[1,0]
	v_pk_add_f32 v[118:119], v[118:119], v[122:123] op_sel_hi:[1,0] neg_lo:[0,1] neg_hi:[0,1]
	s_waitcnt vmcnt(0)
	v_mov_b32_e32 v116, v92
	v_mov_b32_e32 v117, v94
	v_pk_mul_f32 v[124:125], v[116:117], v[124:125]
	v_pk_mul_f32 v[118:119], v[122:123], v[118:119] op_sel:[1,0]
	v_mov_b32_e32 v94, v93
	v_pk_mul_f32 v[92:93], v[94:95], v[118:119]
	v_and_b32_sdwa v118, v125, v245 dst_sel:DWORD dst_unused:UNUSED_PAD src0_sel:WORD_1 src1_sel:DWORD
	v_and_b32_sdwa v119, v124, v245 dst_sel:DWORD dst_unused:UNUSED_PAD src0_sel:WORD_1 src1_sel:DWORD
	v_add3_u32 v124, v124, v119, s68
	v_add3_u32 v118, v125, v118, s68
	v_and_b32_sdwa v119, v93, v245 dst_sel:DWORD dst_unused:UNUSED_PAD src0_sel:WORD_1 src1_sel:DWORD
	v_and_b32_sdwa v125, v92, v245 dst_sel:DWORD dst_unused:UNUSED_PAD src0_sel:WORD_1 src1_sel:DWORD
	v_add3_u32 v93, v93, v119, s68
	v_add3_u32 v92, v92, v125, s68
	v_and_b32_e32 v93, 0xffff0000, v93
	v_and_b32_e32 v92, 0xffff0000, v92
	v_or_b32_sdwa v119, v93, v118 dst_sel:DWORD dst_unused:UNUSED_PAD src0_sel:DWORD src1_sel:WORD_1
	v_or_b32_sdwa v118, v92, v124 dst_sel:DWORD dst_unused:UNUSED_PAD src0_sel:DWORD src1_sel:WORD_1
	v_lshlrev_b32_e32 v93, 16, v121
	v_lshlrev_b32_e32 v92, 16, v120
	v_and_b32_e32 v121, 0xffff0000, v121
	v_and_b32_e32 v120, 0xffff0000, v120
	v_pk_add_f32 v[92:93], v[92:93], v[122:123] op_sel_hi:[1,0] neg_lo:[0,1] neg_hi:[0,1]
	v_pk_add_f32 v[120:121], v[120:121], v[122:123] op_sel_hi:[1,0] neg_lo:[0,1] neg_hi:[0,1]
	v_pk_mul_f32 v[124:125], v[122:123], v[92:93] op_sel:[1,0]
	v_mov_b32_e32 v93, v90
	v_pk_mul_f32 v[120:121], v[122:123], v[120:121] op_sel:[1,0]
	v_mov_b32_e32 v90, v89
	v_mov_b32_e32 v92, v88
	v_pk_mul_f32 v[88:89], v[90:91], v[120:121]
	v_pk_mul_f32 v[124:125], v[92:93], v[124:125]
	v_and_b32_sdwa v122, v89, v245 dst_sel:DWORD dst_unused:UNUSED_PAD src0_sel:WORD_1 src1_sel:DWORD
	v_and_b32_sdwa v123, v88, v245 dst_sel:DWORD dst_unused:UNUSED_PAD src0_sel:WORD_1 src1_sel:DWORD
	v_and_b32_sdwa v120, v125, v245 dst_sel:DWORD dst_unused:UNUSED_PAD src0_sel:WORD_1 src1_sel:DWORD
	v_and_b32_sdwa v121, v124, v245 dst_sel:DWORD dst_unused:UNUSED_PAD src0_sel:WORD_1 src1_sel:DWORD
	v_add3_u32 v89, v89, v122, s68
	v_add3_u32 v88, v88, v123, s68
	v_add3_u32 v121, v124, v121, s68
	v_add3_u32 v120, v125, v120, s68
	v_and_b32_e32 v89, 0xffff0000, v89
	v_and_b32_e32 v88, 0xffff0000, v88
	v_or_b32_sdwa v89, v89, v120 dst_sel:DWORD dst_unused:UNUSED_PAD src0_sel:DWORD src1_sel:WORD_1
	v_or_b32_sdwa v88, v88, v121 dst_sel:DWORD dst_unused:UNUSED_PAD src0_sel:DWORD src1_sel:WORD_1
	ds_write2_b64 v219, v[118:119], v[88:89] offset1:4
	ds_read_b64 v[88:89], v218 offset:10368
	v_lshlrev_b32_e32 v119, 16, v113
	v_lshlrev_b32_e32 v118, 16, v112
	v_and_b32_e32 v113, 0xffff0000, v113
	v_and_b32_e32 v112, 0xffff0000, v112
	s_waitcnt lgkmcnt(0)
	v_pk_add_f32 v[118:119], v[118:119], v[88:89] op_sel_hi:[1,0] neg_lo:[0,1] neg_hi:[0,1]
	v_pk_add_f32 v[112:113], v[112:113], v[88:89] op_sel_hi:[1,0] neg_lo:[0,1] neg_hi:[0,1]
	v_pk_mul_f32 v[118:119], v[88:89], v[118:119] op_sel:[1,0]
	v_pk_mul_f32 v[112:113], v[88:89], v[112:113] op_sel:[1,0]
	v_pk_mul_f32 v[118:119], v[116:117], v[118:119]
	v_pk_mul_f32 v[112:113], v[94:95], v[112:113]
	v_and_b32_sdwa v120, v119, v245 dst_sel:DWORD dst_unused:UNUSED_PAD src0_sel:WORD_1 src1_sel:DWORD
	v_and_b32_sdwa v121, v118, v245 dst_sel:DWORD dst_unused:UNUSED_PAD src0_sel:WORD_1 src1_sel:DWORD
	v_add3_u32 v118, v118, v121, s68
	v_add3_u32 v119, v119, v120, s68
	v_and_b32_sdwa v120, v113, v245 dst_sel:DWORD dst_unused:UNUSED_PAD src0_sel:WORD_1 src1_sel:DWORD
	v_and_b32_sdwa v121, v112, v245 dst_sel:DWORD dst_unused:UNUSED_PAD src0_sel:WORD_1 src1_sel:DWORD
	v_add3_u32 v113, v113, v120, s68
	v_add3_u32 v112, v112, v121, s68
	v_and_b32_e32 v113, 0xffff0000, v113
	v_and_b32_e32 v112, 0xffff0000, v112
	v_or_b32_sdwa v113, v113, v119 dst_sel:DWORD dst_unused:UNUSED_PAD src0_sel:DWORD src1_sel:WORD_1
	v_or_b32_sdwa v112, v112, v118 dst_sel:DWORD dst_unused:UNUSED_PAD src0_sel:DWORD src1_sel:WORD_1
	v_lshlrev_b32_e32 v119, 16, v115
	v_lshlrev_b32_e32 v118, 16, v114
	v_pk_add_f32 v[118:119], v[118:119], v[88:89] op_sel_hi:[1,0] neg_lo:[0,1] neg_hi:[0,1]
	v_and_b32_e32 v115, 0xffff0000, v115
	v_and_b32_e32 v114, 0xffff0000, v114
	v_pk_mul_f32 v[118:119], v[88:89], v[118:119] op_sel:[1,0]
	v_pk_add_f32 v[114:115], v[114:115], v[88:89] op_sel_hi:[1,0] neg_lo:[0,1] neg_hi:[0,1]
	v_pk_mul_f32 v[118:119], v[92:93], v[118:119]
	v_pk_mul_f32 v[88:89], v[88:89], v[114:115] op_sel:[1,0]
	v_and_b32_sdwa v114, v119, v245 dst_sel:DWORD dst_unused:UNUSED_PAD src0_sel:WORD_1 src1_sel:DWORD
	v_pk_mul_f32 v[88:89], v[90:91], v[88:89]
	v_and_b32_sdwa v115, v118, v245 dst_sel:DWORD dst_unused:UNUSED_PAD src0_sel:WORD_1 src1_sel:DWORD
	v_add3_u32 v115, v118, v115, s68
	v_add3_u32 v114, v119, v114, s68
	v_and_b32_sdwa v118, v89, v245 dst_sel:DWORD dst_unused:UNUSED_PAD src0_sel:WORD_1 src1_sel:DWORD
	v_and_b32_sdwa v119, v88, v245 dst_sel:DWORD dst_unused:UNUSED_PAD src0_sel:WORD_1 src1_sel:DWORD
	v_add3_u32 v89, v89, v118, s68
	v_add3_u32 v88, v88, v119, s68
	v_and_b32_e32 v89, 0xffff0000, v89
	v_and_b32_e32 v88, 0xffff0000, v88
	v_or_b32_sdwa v89, v89, v114 dst_sel:DWORD dst_unused:UNUSED_PAD src0_sel:DWORD src1_sel:WORD_1
	v_or_b32_sdwa v88, v88, v115 dst_sel:DWORD dst_unused:UNUSED_PAD src0_sel:DWORD src1_sel:WORD_1
	ds_write2_b64 v219, v[112:113], v[88:89] offset0:160 offset1:164
	ds_read_b64 v[112:113], v218 offset:10496
	v_lshlrev_b32_e32 v89, 16, v109
	v_lshlrev_b32_e32 v88, 16, v108
	v_and_b32_e32 v109, 0xffff0000, v109
	v_and_b32_e32 v108, 0xffff0000, v108
	s_waitcnt lgkmcnt(0)
; #define LAS __attribute__((address_space(3)))
; __device__ __forceinline__ unsigned pk2(float lo, float hi) { return f2bf(lo) | (f2bf(hi) << 16); }
; __device__ __forceinline__ float bflo(unsigned w) { return __uint_as_float(w << 16); }
; __device__ __forceinline__ float bfhi(unsigned w) { return __uint_as_float(w & 0xffff0000u); }
; __device__ __forceinline__ void sgu_item(LAS unsigned char* wl, const bf16* proj, bf16* ymix, const float* vstat, const float* sgu_g, const bf16* Wm, const float* sgu_b, int chunk, int h, int lane) {
;     ...
;         for (int i = 0; i < 8; ++i) { const int s = rsub + 16 * i; const f32x2 ms = st[s]; const v4u w = raw[i];
;             v2u lo, hi; lo.x = pk2((bflo(w.x) - ms.x) * ms.y * g0[0], (bfhi(w.x) - ms.x) * ms.y * g0[1]); lo.y = pk2((bflo(w.y) - ms.x) * ms.y * g0[2], (bfhi(w.y) - ms.x) * ms.y * g0[3]);
;             hi.x = pk2((bflo(w.z) - ms.x) * ms.y * g1[0], (bfhi(w.z) - ms.x) * ms.y * g1[1]); hi.y = pk2((bflo(w.w) - ms.x) * ms.y * g1[2], (bfhi(w.w) - ms.x) * ms.y * g1[3]);
;             *(LAS v2u*)(wl + s * VP2 + (4 * c16) * 2) = lo; *(LAS v2u*)(wl + s * VP2 + (16 + 4 * c16) * 2) = hi; }
	v_pk_add_f32 v[88:89], v[88:89], v[112:113] op_sel_hi:[1,0] neg_lo:[0,1] neg_hi:[0,1]
	v_pk_add_f32 v[108:109], v[108:109], v[112:113] op_sel_hi:[1,0] neg_lo:[0,1] neg_hi:[0,1]
	v_pk_mul_f32 v[88:89], v[112:113], v[88:89] op_sel:[1,0]
	v_pk_mul_f32 v[108:109], v[112:113], v[108:109] op_sel:[1,0]
	v_pk_mul_f32 v[88:89], v[116:117], v[88:89]
	v_pk_mul_f32 v[108:109], v[94:95], v[108:109]
	v_and_b32_sdwa v114, v89, v245 dst_sel:DWORD dst_unused:UNUSED_PAD src0_sel:WORD_1 src1_sel:DWORD
	v_and_b32_sdwa v115, v88, v245 dst_sel:DWORD dst_unused:UNUSED_PAD src0_sel:WORD_1 src1_sel:DWORD
	v_add3_u32 v88, v88, v115, s68
	v_add3_u32 v89, v89, v114, s68
	v_and_b32_sdwa v114, v109, v245 dst_sel:DWORD dst_unused:UNUSED_PAD src0_sel:WORD_1 src1_sel:DWORD
	v_and_b32_sdwa v115, v108, v245 dst_sel:DWORD dst_unused:UNUSED_PAD src0_sel:WORD_1 src1_sel:DWORD
	v_add3_u32 v109, v109, v114, s68
	v_add3_u32 v108, v108, v115, s68
	v_and_b32_e32 v109, 0xffff0000, v109
	v_and_b32_e32 v108, 0xffff0000, v108
	v_or_b32_sdwa v89, v109, v89 dst_sel:DWORD dst_unused:UNUSED_PAD src0_sel:DWORD src1_sel:WORD_1
	v_or_b32_sdwa v88, v108, v88 dst_sel:DWORD dst_unused:UNUSED_PAD src0_sel:DWORD src1_sel:WORD_1
	v_lshlrev_b32_e32 v109, 16, v111
	v_lshlrev_b32_e32 v108, 16, v110
	v_pk_add_f32 v[108:109], v[108:109], v[112:113] op_sel_hi:[1,0] neg_lo:[0,1] neg_hi:[0,1]
	v_and_b32_e32 v111, 0xffff0000, v111
	v_and_b32_e32 v110, 0xffff0000, v110
	v_pk_mul_f32 v[108:109], v[112:113], v[108:109] op_sel:[1,0]
	v_pk_add_f32 v[110:111], v[110:111], v[112:113] op_sel_hi:[1,0] neg_lo:[0,1] neg_hi:[0,1]
	v_pk_mul_f32 v[108:109], v[92:93], v[108:109]
	v_pk_mul_f32 v[110:111], v[112:113], v[110:111] op_sel:[1,0]
	v_and_b32_sdwa v112, v109, v245 dst_sel:DWORD dst_unused:UNUSED_PAD src0_sel:WORD_1 src1_sel:DWORD
	v_pk_mul_f32 v[110:111], v[90:91], v[110:111]
	v_and_b32_sdwa v113, v108, v245 dst_sel:DWORD dst_unused:UNUSED_PAD src0_sel:WORD_1 src1_sel:DWORD
	v_add3_u32 v108, v108, v113, s68
	v_add3_u32 v109, v109, v112, s68
	v_and_b32_sdwa v112, v111, v245 dst_sel:DWORD dst_unused:UNUSED_PAD src0_sel:WORD_1 src1_sel:DWORD
	v_and_b32_sdwa v113, v110, v245 dst_sel:DWORD dst_unused:UNUSED_PAD src0_sel:WORD_1 src1_sel:DWORD
	v_add3_u32 v111, v111, v112, s68
	v_add3_u32 v110, v110, v113, s68
	v_and_b32_e32 v111, 0xffff0000, v111
	v_and_b32_e32 v110, 0xffff0000, v110
	v_or_b32_sdwa v109, v111, v109 dst_sel:DWORD dst_unused:UNUSED_PAD src0_sel:DWORD src1_sel:WORD_1
	v_or_b32_sdwa v108, v110, v108 dst_sel:DWORD dst_unused:UNUSED_PAD src0_sel:DWORD src1_sel:WORD_1
	v_add_u32_e32 v110, 0x800, v219
	ds_write2_b64 v110, v[88:89], v[108:109] offset0:64 offset1:68
	ds_read_b64 v[88:89], v218 offset:10624
	v_lshlrev_b32_e32 v109, 16, v105
	v_lshlrev_b32_e32 v108, 16, v104
	v_and_b32_e32 v105, 0xffff0000, v105
	v_and_b32_e32 v104, 0xffff0000, v104
	s_waitcnt lgkmcnt(0)
	v_pk_add_f32 v[108:109], v[108:109], v[88:89] op_sel_hi:[1,0] neg_lo:[0,1] neg_hi:[0,1]
	v_pk_add_f32 v[104:105], v[104:105], v[88:89] op_sel_hi:[1,0] neg_lo:[0,1] neg_hi:[0,1]
	v_pk_mul_f32 v[108:109], v[88:89], v[108:109] op_sel:[1,0]
	v_pk_mul_f32 v[104:105], v[88:89], v[104:105] op_sel:[1,0]
	v_pk_mul_f32 v[108:109], v[116:117], v[108:109]
	v_pk_mul_f32 v[104:105], v[94:95], v[104:105]
	v_and_b32_sdwa v111, v109, v245 dst_sel:DWORD dst_unused:UNUSED_PAD src0_sel:WORD_1 src1_sel:DWORD
	v_and_b32_sdwa v112, v108, v245 dst_sel:DWORD dst_unused:UNUSED_PAD src0_sel:WORD_1 src1_sel:DWORD
	v_add3_u32 v108, v108, v112, s68
	v_add3_u32 v109, v109, v111, s68
	v_and_b32_sdwa v111, v105, v245 dst_sel:DWORD dst_unused:UNUSED_PAD src0_sel:WORD_1 src1_sel:DWORD
	v_and_b32_sdwa v112, v104, v245 dst_sel:DWORD dst_unused:UNUSED_PAD src0_sel:WORD_1 src1_sel:DWORD
	v_add3_u32 v105, v105, v111, s68
	v_add3_u32 v104, v104, v112, s68
	v_and_b32_e32 v105, 0xffff0000, v105
	v_and_b32_e32 v104, 0xffff0000, v104
	v_or_b32_sdwa v105, v105, v109 dst_sel:DWORD dst_unused:UNUSED_PAD src0_sel:DWORD src1_sel:WORD_1
	v_or_b32_sdwa v104, v104, v108 dst_sel:DWORD dst_unused:UNUSED_PAD src0_sel:DWORD src1_sel:WORD_1
	v_lshlrev_b32_e32 v109, 16, v107
	v_lshlrev_b32_e32 v108, 16, v106
	v_pk_add_f32 v[108:109], v[108:109], v[88:89] op_sel_hi:[1,0] neg_lo:[0,1] neg_hi:[0,1]
	v_and_b32_e32 v107, 0xffff0000, v107
	v_and_b32_e32 v106, 0xffff0000, v106
	v_pk_mul_f32 v[108:109], v[88:89], v[108:109] op_sel:[1,0]
	v_pk_add_f32 v[106:107], v[106:107], v[88:89] op_sel_hi:[1,0] neg_lo:[0,1] neg_hi:[0,1]
	v_pk_mul_f32 v[108:109], v[92:93], v[108:109]
	v_pk_mul_f32 v[88:89], v[88:89], v[106:107] op_sel:[1,0]
	v_and_b32_sdwa v106, v109, v245 dst_sel:DWORD dst_unused:UNUSED_PAD src0_sel:WORD_1 src1_sel:DWORD
	v_pk_mul_f32 v[88:89], v[90:91], v[88:89]
	v_and_b32_sdwa v107, v108, v245 dst_sel:DWORD dst_unused:UNUSED_PAD src0_sel:WORD_1 src1_sel:DWORD
	v_add3_u32 v107, v108, v107, s68
	v_add3_u32 v106, v109, v106, s68
	v_and_b32_sdwa v108, v89, v245 dst_sel:DWORD dst_unused:UNUSED_PAD src0_sel:WORD_1 src1_sel:DWORD
	v_and_b32_sdwa v109, v88, v245 dst_sel:DWORD dst_unused:UNUSED_PAD src0_sel:WORD_1 src1_sel:DWORD
	v_add3_u32 v89, v89, v108, s68
	v_add3_u32 v88, v88, v109, s68
	v_and_b32_e32 v89, 0xffff0000, v89
	v_and_b32_e32 v88, 0xffff0000, v88
	v_or_b32_sdwa v89, v89, v106 dst_sel:DWORD dst_unused:UNUSED_PAD src0_sel:DWORD src1_sel:WORD_1
	v_or_b32_sdwa v88, v88, v107 dst_sel:DWORD dst_unused:UNUSED_PAD src0_sel:DWORD src1_sel:WORD_1
	ds_write2_b64 v110, v[104:105], v[88:89] offset0:224 offset1:228
	ds_read_b64 v[104:105], v218 offset:10752
	v_lshlrev_b32_e32 v89, 16, v101
	v_lshlrev_b32_e32 v88, 16, v100
	v_and_b32_e32 v101, 0xffff0000, v101
	v_and_b32_e32 v100, 0xffff0000, v100
	s_waitcnt lgkmcnt(0)
; #define LAS __attribute__((address_space(3)))
; __device__ __forceinline__ unsigned pk2(float lo, float hi) { return f2bf(lo) | (f2bf(hi) << 16); }
; __device__ __forceinline__ float bflo(unsigned w) { return __uint_as_float(w << 16); }
; __device__ __forceinline__ float bfhi(unsigned w) { return __uint_as_float(w & 0xffff0000u); }
; __device__ __forceinline__ void sgu_item(LAS unsigned char* wl, const bf16* proj, bf16* ymix, const float* vstat, const float* sgu_g, const bf16* Wm, const float* sgu_b, int chunk, int h, int lane) {
;     ...
;         for (int i = 0; i < 8; ++i) { const int s = rsub + 16 * i; const f32x2 ms = st[s]; const v4u w = raw[i];
;             v2u lo, hi; lo.x = pk2((bflo(w.x) - ms.x) * ms.y * g0[0], (bfhi(w.x) - ms.x) * ms.y * g0[1]); lo.y = pk2((bflo(w.y) - ms.x) * ms.y * g0[2], (bfhi(w.y) - ms.x) * ms.y * g0[3]);
;             hi.x = pk2((bflo(w.z) - ms.x) * ms.y * g1[0], (bfhi(w.z) - ms.x) * ms.y * g1[1]); hi.y = pk2((bflo(w.w) - ms.x) * ms.y * g1[2], (bfhi(w.w) - ms.x) * ms.y * g1[3]);
;             *(LAS v2u*)(wl + s * VP2 + (4 * c16) * 2) = lo; *(LAS v2u*)(wl + s * VP2 + (16 + 4 * c16) * 2) = hi; }
	v_pk_add_f32 v[88:89], v[88:89], v[104:105] op_sel_hi:[1,0] neg_lo:[0,1] neg_hi:[0,1]
	v_pk_add_f32 v[100:101], v[100:101], v[104:105] op_sel_hi:[1,0] neg_lo:[0,1] neg_hi:[0,1]
	v_pk_mul_f32 v[88:89], v[104:105], v[88:89] op_sel:[1,0]
	v_pk_mul_f32 v[100:101], v[104:105], v[100:101] op_sel:[1,0]
	v_pk_mul_f32 v[88:89], v[116:117], v[88:89]
	v_pk_mul_f32 v[100:101], v[94:95], v[100:101]
	v_and_b32_sdwa v106, v89, v245 dst_sel:DWORD dst_unused:UNUSED_PAD src0_sel:WORD_1 src1_sel:DWORD
	v_and_b32_sdwa v107, v88, v245 dst_sel:DWORD dst_unused:UNUSED_PAD src0_sel:WORD_1 src1_sel:DWORD
	v_add3_u32 v88, v88, v107, s68
	v_add3_u32 v89, v89, v106, s68
	v_and_b32_sdwa v106, v101, v245 dst_sel:DWORD dst_unused:UNUSED_PAD src0_sel:WORD_1 src1_sel:DWORD
	v_and_b32_sdwa v107, v100, v245 dst_sel:DWORD dst_unused:UNUSED_PAD src0_sel:WORD_1 src1_sel:DWORD
	v_add3_u32 v101, v101, v106, s68
	v_add3_u32 v100, v100, v107, s68
	v_and_b32_e32 v101, 0xffff0000, v101
	v_and_b32_e32 v100, 0xffff0000, v100
	v_or_b32_sdwa v89, v101, v89 dst_sel:DWORD dst_unused:UNUSED_PAD src0_sel:DWORD src1_sel:WORD_1
	v_or_b32_sdwa v88, v100, v88 dst_sel:DWORD dst_unused:UNUSED_PAD src0_sel:DWORD src1_sel:WORD_1
	v_lshlrev_b32_e32 v101, 16, v103
	v_lshlrev_b32_e32 v100, 16, v102
	v_pk_add_f32 v[100:101], v[100:101], v[104:105] op_sel_hi:[1,0] neg_lo:[0,1] neg_hi:[0,1]
	v_and_b32_e32 v103, 0xffff0000, v103
	v_and_b32_e32 v102, 0xffff0000, v102
	v_pk_mul_f32 v[100:101], v[104:105], v[100:101] op_sel:[1,0]
	v_pk_add_f32 v[102:103], v[102:103], v[104:105] op_sel_hi:[1,0] neg_lo:[0,1] neg_hi:[0,1]
	v_pk_mul_f32 v[100:101], v[92:93], v[100:101]
	v_pk_mul_f32 v[102:103], v[104:105], v[102:103] op_sel:[1,0]
	v_and_b32_sdwa v104, v101, v245 dst_sel:DWORD dst_unused:UNUSED_PAD src0_sel:WORD_1 src1_sel:DWORD
	v_pk_mul_f32 v[102:103], v[90:91], v[102:103]
	v_and_b32_sdwa v105, v100, v245 dst_sel:DWORD dst_unused:UNUSED_PAD src0_sel:WORD_1 src1_sel:DWORD
	v_add3_u32 v100, v100, v105, s68
	v_add3_u32 v101, v101, v104, s68
	v_and_b32_sdwa v104, v103, v245 dst_sel:DWORD dst_unused:UNUSED_PAD src0_sel:WORD_1 src1_sel:DWORD
	v_and_b32_sdwa v105, v102, v245 dst_sel:DWORD dst_unused:UNUSED_PAD src0_sel:WORD_1 src1_sel:DWORD
	v_add3_u32 v103, v103, v104, s68
	v_add3_u32 v102, v102, v105, s68
	v_and_b32_e32 v103, 0xffff0000, v103
	v_and_b32_e32 v102, 0xffff0000, v102
	v_or_b32_sdwa v101, v103, v101 dst_sel:DWORD dst_unused:UNUSED_PAD src0_sel:DWORD src1_sel:WORD_1
	v_or_b32_sdwa v100, v102, v100 dst_sel:DWORD dst_unused:UNUSED_PAD src0_sel:DWORD src1_sel:WORD_1
	v_add_u32_e32 v102, 0x1000, v219
	ds_write2_b64 v102, v[88:89], v[100:101] offset0:128 offset1:132
	ds_read_b64 v[88:89], v218 offset:10880
	v_lshlrev_b32_e32 v101, 16, v97
	v_lshlrev_b32_e32 v100, 16, v96
	v_and_b32_e32 v97, 0xffff0000, v97
	v_and_b32_e32 v96, 0xffff0000, v96
	s_waitcnt lgkmcnt(0)
	v_pk_add_f32 v[100:101], v[100:101], v[88:89] op_sel_hi:[1,0] neg_lo:[0,1] neg_hi:[0,1]
	v_pk_add_f32 v[96:97], v[96:97], v[88:89] op_sel_hi:[1,0] neg_lo:[0,1] neg_hi:[0,1]
	v_pk_mul_f32 v[100:101], v[88:89], v[100:101] op_sel:[1,0]
	v_pk_mul_f32 v[96:97], v[88:89], v[96:97] op_sel:[1,0]
	v_pk_mul_f32 v[100:101], v[116:117], v[100:101]
	v_pk_mul_f32 v[96:97], v[94:95], v[96:97]
	v_and_b32_sdwa v102, v101, v245 dst_sel:DWORD dst_unused:UNUSED_PAD src0_sel:WORD_1 src1_sel:DWORD
	v_and_b32_sdwa v103, v100, v245 dst_sel:DWORD dst_unused:UNUSED_PAD src0_sel:WORD_1 src1_sel:DWORD
	v_add3_u32 v100, v100, v103, s68
	v_add3_u32 v101, v101, v102, s68
	v_and_b32_sdwa v102, v97, v245 dst_sel:DWORD dst_unused:UNUSED_PAD src0_sel:WORD_1 src1_sel:DWORD
	v_and_b32_sdwa v103, v96, v245 dst_sel:DWORD dst_unused:UNUSED_PAD src0_sel:WORD_1 src1_sel:DWORD
	v_add3_u32 v97, v97, v102, s68
	v_add3_u32 v96, v96, v103, s68
	v_and_b32_e32 v97, 0xffff0000, v97
	v_and_b32_e32 v96, 0xffff0000, v96
	v_or_b32_sdwa v97, v97, v101 dst_sel:DWORD dst_unused:UNUSED_PAD src0_sel:DWORD src1_sel:WORD_1
	v_or_b32_sdwa v96, v96, v100 dst_sel:DWORD dst_unused:UNUSED_PAD src0_sel:DWORD src1_sel:WORD_1
	v_lshlrev_b32_e32 v101, 16, v99
	v_lshlrev_b32_e32 v100, 16, v98
	v_pk_add_f32 v[100:101], v[100:101], v[88:89] op_sel_hi:[1,0] neg_lo:[0,1] neg_hi:[0,1]
	v_and_b32_e32 v99, 0xffff0000, v99
	v_and_b32_e32 v98, 0xffff0000, v98
	v_pk_mul_f32 v[100:101], v[88:89], v[100:101] op_sel:[1,0]
	v_pk_add_f32 v[98:99], v[98:99], v[88:89] op_sel_hi:[1,0] neg_lo:[0,1] neg_hi:[0,1]
	v_pk_mul_f32 v[100:101], v[92:93], v[100:101]
	v_pk_mul_f32 v[88:89], v[88:89], v[98:99] op_sel:[1,0]
	v_and_b32_sdwa v98, v101, v245 dst_sel:DWORD dst_unused:UNUSED_PAD src0_sel:WORD_1 src1_sel:DWORD
	v_pk_mul_f32 v[88:89], v[90:91], v[88:89]
	v_and_b32_sdwa v99, v100, v245 dst_sel:DWORD dst_unused:UNUSED_PAD src0_sel:WORD_1 src1_sel:DWORD
	v_add3_u32 v99, v100, v99, s68
	v_add3_u32 v98, v101, v98, s68
	v_and_b32_sdwa v100, v89, v245 dst_sel:DWORD dst_unused:UNUSED_PAD src0_sel:WORD_1 src1_sel:DWORD
	v_and_b32_sdwa v101, v88, v245 dst_sel:DWORD dst_unused:UNUSED_PAD src0_sel:WORD_1 src1_sel:DWORD
	v_add3_u32 v89, v89, v100, s68
	v_add3_u32 v88, v88, v101, s68
	v_and_b32_e32 v89, 0xffff0000, v89
	v_and_b32_e32 v88, 0xffff0000, v88
	v_or_b32_sdwa v89, v89, v98 dst_sel:DWORD dst_unused:UNUSED_PAD src0_sel:DWORD src1_sel:WORD_1
	v_or_b32_sdwa v88, v88, v99 dst_sel:DWORD dst_unused:UNUSED_PAD src0_sel:DWORD src1_sel:WORD_1
	v_add_u32_e32 v98, 0x1800, v219
	ds_write2_b64 v98, v[96:97], v[88:89] offset0:32 offset1:36
	ds_read_b64 v[88:89], v218 offset:11008
	v_lshlrev_b32_e32 v97, 16, v85
	v_lshlrev_b32_e32 v96, 16, v84
	v_and_b32_e32 v85, 0xffff0000, v85
	v_and_b32_e32 v84, 0xffff0000, v84
	s_waitcnt lgkmcnt(0)
; #define LAS __attribute__((address_space(3)))
; __device__ __forceinline__ unsigned pk2(float lo, float hi) { return f2bf(lo) | (f2bf(hi) << 16); }
; __device__ __forceinline__ float bflo(unsigned w) { return __uint_as_float(w << 16); }
; __device__ __forceinline__ float bfhi(unsigned w) { return __uint_as_float(w & 0xffff0000u); }
; __device__ __forceinline__ void sgu_item(LAS unsigned char* wl, const bf16* proj, bf16* ymix, const float* vstat, const float* sgu_g, const bf16* Wm, const float* sgu_b, int chunk, int h, int lane) {
;     ...
;         for (int i = 0; i < 8; ++i) { const int s = rsub + 16 * i; const f32x2 ms = st[s]; const v4u w = raw[i];
;             v2u lo, hi; lo.x = pk2((bflo(w.x) - ms.x) * ms.y * g0[0], (bfhi(w.x) - ms.x) * ms.y * g0[1]); lo.y = pk2((bflo(w.y) - ms.x) * ms.y * g0[2], (bfhi(w.y) - ms.x) * ms.y * g0[3]);
;             hi.x = pk2((bflo(w.z) - ms.x) * ms.y * g1[0], (bfhi(w.z) - ms.x) * ms.y * g1[1]); hi.y = pk2((bflo(w.w) - ms.x) * ms.y * g1[2], (bfhi(w.w) - ms.x) * ms.y * g1[3]);
;             *(LAS v2u*)(wl + s * VP2 + (4 * c16) * 2) = lo; *(LAS v2u*)(wl + s * VP2 + (16 + 4 * c16) * 2) = hi; }
;         v4u uu8[8];
; #pragma unroll
;         for (int tb = 0; tb < 8; ++tb) uu8[tb] = __builtin_nontemporal_load((const v4u*)(proj + (R0 + 16 * tb + r) * DIN + 512 + colv + 8 * q));
	v_pk_add_f32 v[96:97], v[96:97], v[88:89] op_sel_hi:[1,0] neg_lo:[0,1] neg_hi:[0,1]
	v_pk_add_f32 v[84:85], v[84:85], v[88:89] op_sel_hi:[1,0] neg_lo:[0,1] neg_hi:[0,1]
	v_pk_mul_f32 v[96:97], v[88:89], v[96:97] op_sel:[1,0]
	v_pk_mul_f32 v[84:85], v[88:89], v[84:85] op_sel:[1,0]
	v_pk_mul_f32 v[96:97], v[116:117], v[96:97]
	v_pk_mul_f32 v[84:85], v[94:95], v[84:85]
	v_and_b32_sdwa v99, v97, v245 dst_sel:DWORD dst_unused:UNUSED_PAD src0_sel:WORD_1 src1_sel:DWORD
	v_and_b32_sdwa v100, v96, v245 dst_sel:DWORD dst_unused:UNUSED_PAD src0_sel:WORD_1 src1_sel:DWORD
	v_add3_u32 v96, v96, v100, s68
	v_add3_u32 v97, v97, v99, s68
	v_and_b32_sdwa v99, v85, v245 dst_sel:DWORD dst_unused:UNUSED_PAD src0_sel:WORD_1 src1_sel:DWORD
	v_and_b32_sdwa v100, v84, v245 dst_sel:DWORD dst_unused:UNUSED_PAD src0_sel:WORD_1 src1_sel:DWORD
	v_add3_u32 v85, v85, v99, s68
	v_add3_u32 v84, v84, v100, s68
	v_and_b32_e32 v85, 0xffff0000, v85
	v_and_b32_e32 v84, 0xffff0000, v84
	v_or_b32_sdwa v85, v85, v97 dst_sel:DWORD dst_unused:UNUSED_PAD src0_sel:DWORD src1_sel:WORD_1
	v_or_b32_sdwa v84, v84, v96 dst_sel:DWORD dst_unused:UNUSED_PAD src0_sel:DWORD src1_sel:WORD_1
	v_lshlrev_b32_e32 v97, 16, v87
	v_lshlrev_b32_e32 v96, 16, v86
	v_pk_add_f32 v[96:97], v[96:97], v[88:89] op_sel_hi:[1,0] neg_lo:[0,1] neg_hi:[0,1]
	v_and_b32_e32 v87, 0xffff0000, v87
	v_and_b32_e32 v86, 0xffff0000, v86
	v_pk_mul_f32 v[96:97], v[88:89], v[96:97] op_sel:[1,0]
	v_pk_add_f32 v[86:87], v[86:87], v[88:89] op_sel_hi:[1,0] neg_lo:[0,1] neg_hi:[0,1]
	v_pk_mul_f32 v[96:97], v[92:93], v[96:97]
	v_pk_mul_f32 v[86:87], v[88:89], v[86:87] op_sel:[1,0]
	v_and_b32_sdwa v88, v97, v245 dst_sel:DWORD dst_unused:UNUSED_PAD src0_sel:WORD_1 src1_sel:DWORD
	v_pk_mul_f32 v[86:87], v[90:91], v[86:87]
	v_and_b32_sdwa v89, v96, v245 dst_sel:DWORD dst_unused:UNUSED_PAD src0_sel:WORD_1 src1_sel:DWORD
	v_add3_u32 v89, v96, v89, s68
	v_add3_u32 v88, v97, v88, s68
	v_and_b32_sdwa v96, v87, v245 dst_sel:DWORD dst_unused:UNUSED_PAD src0_sel:WORD_1 src1_sel:DWORD
	v_and_b32_sdwa v97, v86, v245 dst_sel:DWORD dst_unused:UNUSED_PAD src0_sel:WORD_1 src1_sel:DWORD
	v_add3_u32 v87, v87, v96, s68
	v_add3_u32 v86, v86, v97, s68
	v_and_b32_e32 v87, 0xffff0000, v87
	v_and_b32_e32 v86, 0xffff0000, v86
	v_or_b32_sdwa v87, v87, v88 dst_sel:DWORD dst_unused:UNUSED_PAD src0_sel:DWORD src1_sel:WORD_1
	v_or_b32_sdwa v86, v86, v89 dst_sel:DWORD dst_unused:UNUSED_PAD src0_sel:DWORD src1_sel:WORD_1
	ds_write2_b64 v98, v[84:85], v[86:87] offset0:192 offset1:196
	ds_read_b64 v[84:85], v218 offset:11136
	v_lshlrev_b32_e32 v87, 16, v81
	v_lshlrev_b32_e32 v86, 16, v80
	v_and_b32_e32 v81, 0xffff0000, v81
	v_and_b32_e32 v80, 0xffff0000, v80
	s_waitcnt lgkmcnt(0)
	v_pk_add_f32 v[86:87], v[86:87], v[84:85] op_sel_hi:[1,0] neg_lo:[0,1] neg_hi:[0,1]
	v_pk_add_f32 v[80:81], v[80:81], v[84:85] op_sel_hi:[1,0] neg_lo:[0,1] neg_hi:[0,1]
	v_pk_mul_f32 v[86:87], v[84:85], v[86:87] op_sel:[1,0]
	v_pk_mul_f32 v[80:81], v[84:85], v[80:81] op_sel:[1,0]
	v_pk_mul_f32 v[86:87], v[116:117], v[86:87]
	v_pk_mul_f32 v[80:81], v[94:95], v[80:81]
	v_and_b32_sdwa v88, v87, v245 dst_sel:DWORD dst_unused:UNUSED_PAD src0_sel:WORD_1 src1_sel:DWORD
	v_and_b32_sdwa v89, v86, v245 dst_sel:DWORD dst_unused:UNUSED_PAD src0_sel:WORD_1 src1_sel:DWORD
	v_add3_u32 v86, v86, v89, s68
	v_add3_u32 v87, v87, v88, s68
	v_and_b32_sdwa v88, v81, v245 dst_sel:DWORD dst_unused:UNUSED_PAD src0_sel:WORD_1 src1_sel:DWORD
	v_and_b32_sdwa v89, v80, v245 dst_sel:DWORD dst_unused:UNUSED_PAD src0_sel:WORD_1 src1_sel:DWORD
	v_add3_u32 v81, v81, v88, s68
	v_add3_u32 v80, v80, v89, s68
	v_and_b32_e32 v81, 0xffff0000, v81
	v_and_b32_e32 v80, 0xffff0000, v80
	v_or_b32_sdwa v81, v81, v87 dst_sel:DWORD dst_unused:UNUSED_PAD src0_sel:DWORD src1_sel:WORD_1
	v_or_b32_sdwa v80, v80, v86 dst_sel:DWORD dst_unused:UNUSED_PAD src0_sel:DWORD src1_sel:WORD_1
	v_lshlrev_b32_e32 v87, 16, v83
	v_lshlrev_b32_e32 v86, 16, v82
	v_pk_add_f32 v[86:87], v[86:87], v[84:85] op_sel_hi:[1,0] neg_lo:[0,1] neg_hi:[0,1]
	v_and_b32_e32 v83, 0xffff0000, v83
	v_and_b32_e32 v82, 0xffff0000, v82
	v_pk_mul_f32 v[86:87], v[84:85], v[86:87] op_sel:[1,0]
	v_pk_add_f32 v[82:83], v[82:83], v[84:85] op_sel_hi:[1,0] neg_lo:[0,1] neg_hi:[0,1]
	v_pk_mul_f32 v[86:87], v[92:93], v[86:87]
	v_pk_mul_f32 v[82:83], v[84:85], v[82:83] op_sel:[1,0]
	v_and_b32_sdwa v84, v87, v245 dst_sel:DWORD dst_unused:UNUSED_PAD src0_sel:WORD_1 src1_sel:DWORD
	v_pk_mul_f32 v[82:83], v[90:91], v[82:83]
	v_and_b32_sdwa v85, v86, v245 dst_sel:DWORD dst_unused:UNUSED_PAD src0_sel:WORD_1 src1_sel:DWORD
	v_add3_u32 v85, v86, v85, s68
	v_add3_u32 v84, v87, v84, s68
	v_and_b32_sdwa v86, v83, v245 dst_sel:DWORD dst_unused:UNUSED_PAD src0_sel:WORD_1 src1_sel:DWORD
	v_and_b32_sdwa v87, v82, v245 dst_sel:DWORD dst_unused:UNUSED_PAD src0_sel:WORD_1 src1_sel:DWORD
	v_add3_u32 v83, v83, v86, s68
	v_add3_u32 v82, v82, v87, s68
	v_and_b32_e32 v83, 0xffff0000, v83
	v_and_b32_e32 v82, 0xffff0000, v82
	v_or_b32_sdwa v83, v83, v84 dst_sel:DWORD dst_unused:UNUSED_PAD src0_sel:DWORD src1_sel:WORD_1
	v_or_b32_sdwa v82, v82, v85 dst_sel:DWORD dst_unused:UNUSED_PAD src0_sel:DWORD src1_sel:WORD_1
	v_add_u32_e32 v84, 0x2000, v219
	ds_write2_b64 v84, v[80:81], v[82:83] offset0:96 offset1:100
	v_lshl_add_u64 v[80:81], v[188:189], 0, s[20:21]
	v_add_co_u32_e32 v82, vcc, s0, v80
	s_mov_b32 s0, 0xf10c000
	s_nop 0
	v_addc_co_u32_e32 v83, vcc, 0, v81, vcc
	global_load_dwordx4 v[104:107], v[82:83], off offset:1024
	v_add_co_u32_e32 v82, vcc, s0, v80
	s_mov_b32 s0, 0xf118000
	s_nop 0
	v_addc_co_u32_e32 v83, vcc, 0, v81, vcc
	global_load_dwordx4 v[100:103], v[82:83], off offset:1024
	v_add_co_u32_e32 v82, vcc, s0, v80
	s_mov_b32 s0, 0xf130000
	s_nop 0
	v_addc_co_u32_e32 v83, vcc, 0, v81, vcc
	global_load_dwordx4 v[96:99], v[82:83], off offset:1024
	v_lshl_add_u64 v[82:83], v[190:191], 0, s[20:21]
	global_load_dwordx4 v[92:95], v[82:83], off
	v_add_co_u32_e32 v82, vcc, s0, v80
	s_mov_b32 s0, 0xf13c000
	s_nop 0
	v_addc_co_u32_e32 v83, vcc, 0, v81, vcc
	global_load_dwordx4 v[88:91], v[82:83], off offset:1024
	v_add_co_u32_e32 v82, vcc, s0, v80
	s_mov_b32 s0, 0xf148000
	s_nop 0
	v_addc_co_u32_e32 v83, vcc, 0, v81, vcc
	global_load_dwordx4 v[84:87], v[82:83], off offset:1024
	v_add_co_u32_e32 v80, vcc, s0, v80
	v_lshl_add_u64 v[108:109], v[186:187], 0, s[20:21]
	s_nop 0
	v_addc_co_u32_e32 v81, vcc, 0, v81, vcc
	global_load_dwordx4 v[80:83], v[80:81], off offset:1024
	s_mov_b32 s0, 0x10900000
	global_load_dwordx4 v[108:111], v[108:109], off
	s_waitcnt lgkmcnt(0)
; #define LAS __attribute__((address_space(3)))
; #define MFMA16(a, b, c) __builtin_amdgcn_mfma_f32_16x16x32_bf16((a), (b), (c), 0, 0, 0)
; __device__ __forceinline__ unsigned pk2(float lo, float hi) { return f2bf(lo) | (f2bf(hi) << 16); }
; __device__ __forceinline__ float bflo(unsigned w) { return __uint_as_float(w << 16); }
; __device__ __forceinline__ float bfhi(unsigned w) { return __uint_as_float(w & 0xffff0000u); }
; __device__ __forceinline__ void sgu_item(LAS unsigned char* wl, const bf16* proj, bf16* ymix, const float* vstat, const float* sgu_g, const bf16* Wm, const float* sgu_b, int chunk, int h, int lane) {
;     ...
;         for (int n = 0; n < 2; ++n) {
;             f32x4 z[8];
; #pragma unroll
;             for (int tb = 0; tb < 8; ++tb) z[tb] = (f32x4){0.f, 0.f, 0.f, 0.f};
;             int f = 0;
; #pragma unroll
;             for (int ks = 0; ks < 4; ++ks) {
;                 LAS unsigned char* ad = wl + (ks * 32 + 8 * q + (r >> 2)) * VP2 + (16 * n) * 2 + 8 * (r & 3);
;                 const s16x4 lo = __builtin_bit_cast(s16x4, __builtin_amdgcn_ds_read_tr16_b64_v4i16((LAS s16x4*)ad));
;                 const s16x4 hi = __builtin_bit_cast(s16x4, __builtin_amdgcn_ds_read_tr16_b64_v4i16((LAS s16x4*)(ad + 4 * VP2)));
;                 const bf16x8 vf = __builtin_shufflevector(lo, hi, 0, 1, 2, 3, 4, 5, 6, 7);
; #pragma unroll
;                 for (int tb = 2 * ks; tb < 8; ++tb) z[tb] = MFMA16(vf, wmf[f++], z[tb]);
;             }
; #pragma unroll
;             for (int tb = 0; tb < 8; ++tb) { const v4u uu = uu8[tb]; const unsigned ux = n == 0 ? uu.x : uu.z, uy = n == 0 ? uu.y : uu.w;
;                 v2u o; o.x = pk2(bflo(ux) * (z[tb][0] + bias[tb]), bfhi(ux) * (z[tb][1] + bias[tb])); o.y = pk2(bflo(uy) * (z[tb][2] + bias[tb]), bfhi(uy) * (z[tb][3] + bias[tb]));
;                 if (n == 0) olo[tb] = o;
	ds_read_b64_tr_b16 v[116:117], v220 offset:320
	ds_read_b64_tr_b16 v[114:115], v220
	ds_read_b64_tr_b16 v[112:113], v220 offset:32
	ds_read_b64_tr_b16 v[208:209], v220 offset:2560
	ds_read_b64_tr_b16 v[210:211], v220 offset:2880
	s_waitcnt lgkmcnt(0)
	v_mfma_f32_16x16x32_bf16 v[118:121], v[114:117], v[0:3], 0
	v_mfma_f32_16x16x32_bf16 v[122:125], v[114:117], v[4:7], 0
	s_nop 6
	v_mov_b32_e32 v138, v119
	v_mov_b32_e32 v119, v120
	v_pk_add_f32 v[118:119], v[162:163], v[118:119]
	v_mfma_f32_16x16x32_bf16 v[126:129], v[114:117], v[8:11], 0
	v_mov_b32_e32 v139, v121
	v_pk_add_f32 v[138:139], v[162:163], v[138:139]
	v_mfma_f32_16x16x32_bf16 v[130:133], v[114:117], v[16:19], 0
	v_mfma_f32_16x16x32_bf16 v[134:137], v[114:117], v[24:27], 0
	v_mfma_f32_16x16x32_bf16 v[200:203], v[114:117], v[48:51], 0
	v_mfma_f32_16x16x32_bf16 v[204:207], v[114:117], v[32:35], 0
	v_mfma_f32_16x16x32_bf16 v[114:117], v[114:117], v[40:43], 0
	v_mfma_f32_16x16x32_bf16 v[126:129], v[208:211], v[12:15], v[126:129]
	v_mfma_f32_16x16x32_bf16 v[130:133], v[208:211], v[20:23], v[130:133]
	v_mfma_f32_16x16x32_bf16 v[134:137], v[208:211], v[28:31], v[134:137]
	v_mfma_f32_16x16x32_bf16 v[200:203], v[208:211], v[56:59], v[200:203]
	v_mfma_f32_16x16x32_bf16 v[204:207], v[208:211], v[36:39], v[204:207]
	v_mfma_f32_16x16x32_bf16 v[114:117], v[208:211], v[44:47], v[114:117]
	ds_read_b64_tr_b16 v[208:209], v220 offset:5120
	ds_read_b64_tr_b16 v[210:211], v220 offset:5440
	s_waitcnt lgkmcnt(0)
	v_mfma_f32_16x16x32_bf16 v[222:225], v[208:211], v[60:63], v[200:203]
	v_mfma_f32_16x16x32_bf16 v[200:203], v[208:211], v[64:67], v[204:207]
	s_nop 2
	ds_read_b64_tr_b16 v[204:205], v220 offset:7680
	ds_read_b64_tr_b16 v[206:207], v220 offset:8000
	s_waitcnt lgkmcnt(0)
	v_mfma_f32_16x16x32_bf16 v[226:229], v[204:207], v[68:71], v[200:203]
	s_waitcnt vmcnt(0)
	s_nop 1
	v_and_b32_e32 v201, 0xffff0000, v105
	v_and_b32_e32 v200, 0xffff0000, v104
	v_lshlrev_b32_e32 v105, 16, v105
	v_lshlrev_b32_e32 v104, 16, v104
	v_pk_mul_f32 v[214:215], v[118:119], v[104:105]
	v_mov_b32_e32 v104, v123
	v_mov_b32_e32 v105, v125
	v_pk_add_f32 v[104:105], v[164:165], v[104:105]
	v_and_b32_e32 v119, 0xffff0000, v101
	v_and_b32_e32 v118, 0xffff0000, v100
	v_mov_b32_e32 v123, v124
	v_mfma_f32_16x16x32_bf16 v[114:117], v[208:211], v[72:75], v[114:117]
	v_mul_f32_e64 v212, v104, v118
	v_mul_f32_e64 v213, v105, v119
	v_pk_add_f32 v[104:105], v[164:165], v[122:123]
	v_lshlrev_b32_e32 v101, 16, v101
	v_lshlrev_b32_e32 v100, 16, v100
	v_mfma_f32_16x16x32_bf16 v[134:137], v[208:211], v[52:55], v[134:137]
	v_mul_f32_e64 v210, v104, v100
	v_mul_f32_e64 v211, v105, v101
	v_mov_b32_e32 v100, v127
	v_mov_b32_e32 v101, v129
	v_pk_add_f32 v[100:101], v[166:167], v[100:101]
	v_and_b32_e32 v105, 0xffff0000, v97
	v_and_b32_e32 v104, 0xffff0000, v96
	v_mov_b32_e32 v127, v128
	v_pk_mul_f32 v[208:209], v[100:101], v[104:105]
	v_pk_add_f32 v[100:101], v[166:167], v[126:127]
	v_lshlrev_b32_e32 v97, 16, v97
	v_lshlrev_b32_e32 v96, 16, v96
	v_mfma_f32_16x16x32_bf16 v[114:117], v[204:207], v[76:79], v[114:117]
	v_mul_f32_e64 v206, v100, v96
	v_mul_f32_e64 v207, v101, v97
	v_mov_b32_e32 v96, v131
	v_mov_b32_e32 v97, v133
	v_pk_add_f32 v[96:97], v[168:169], v[96:97]
	v_and_b32_e32 v101, 0xffff0000, v93
	v_and_b32_e32 v100, 0xffff0000, v92
	v_mov_b32_e32 v131, v132
	v_pk_mul_f32 v[204:205], v[96:97], v[100:101]
	v_pk_add_f32 v[96:97], v[168:169], v[130:131]
	v_lshlrev_b32_e32 v93, 16, v93
	v_lshlrev_b32_e32 v92, 16, v92
	v_pk_mul_f32 v[202:203], v[96:97], v[92:93]
	v_mov_b32_e32 v92, v135
	v_mov_b32_e32 v93, v137
	v_pk_add_f32 v[92:93], v[170:171], v[92:93]
	v_and_b32_e32 v97, 0xffff0000, v89
	v_and_b32_e32 v96, 0xffff0000, v88
	v_mov_b32_e32 v135, v136
	v_pk_mul_f32 v[216:217], v[138:139], v[200:201]
	v_pk_mul_f32 v[200:201], v[92:93], v[96:97]
	v_pk_add_f32 v[92:93], v[170:171], v[134:135]
	v_lshlrev_b32_e32 v89, 16, v89
	v_lshlrev_b32_e32 v88, 16, v88
	v_pk_mul_f32 v[104:105], v[92:93], v[88:89]
	v_mov_b32_e32 v88, v223
	v_mov_b32_e32 v89, v225
	v_pk_add_f32 v[88:89], v[172:173], v[88:89]
	v_and_b32_e32 v93, 0xffff0000, v85
	v_and_b32_e32 v92, 0xffff0000, v84
	v_mov_b32_e32 v223, v224
	v_pk_mul_f32 v[100:101], v[88:89], v[92:93]
	v_pk_add_f32 v[88:89], v[172:173], v[222:223]
	v_lshlrev_b32_e32 v85, 16, v85
	v_lshlrev_b32_e32 v84, 16, v84
	v_pk_mul_f32 v[96:97], v[88:89], v[84:85]
	v_mov_b32_e32 v84, v227
	v_mov_b32_e32 v85, v229
	v_pk_add_f32 v[84:85], v[174:175], v[84:85]
	v_and_b32_e32 v89, 0xffff0000, v81
	v_and_b32_e32 v88, 0xffff0000, v80
	v_mov_b32_e32 v227, v228
	v_pk_mul_f32 v[92:93], v[84:85], v[88:89]
	v_pk_add_f32 v[84:85], v[174:175], v[226:227]
	v_lshlrev_b32_e32 v81, 16, v81
	v_lshlrev_b32_e32 v80, 16, v80
	v_pk_mul_f32 v[80:81], v[84:85], v[80:81]
	v_mov_b32_e32 v84, v115
	v_mov_b32_e32 v85, v117
	v_pk_add_f32 v[84:85], v[176:177], v[84:85]
	v_and_b32_e32 v89, 0xffff0000, v109
	v_and_b32_e32 v88, 0xffff0000, v108
	v_mov_b32_e32 v115, v116
	v_pk_mul_f32 v[88:89], v[84:85], v[88:89]
	v_pk_add_f32 v[84:85], v[176:177], v[114:115]
	ds_read_b64_tr_b16 v[114:115], v220 offset:352
	ds_read_b64_tr_b16 v[234:235], v220 offset:2592
	ds_read_b64_tr_b16 v[236:237], v220 offset:2912
	s_waitcnt lgkmcnt(2)
	v_mfma_f32_16x16x32_bf16 v[120:123], v[112:115], v[16:19], 0
	v_lshlrev_b32_e32 v109, 16, v109
	v_lshlrev_b32_e32 v108, 16, v108
	v_pk_mul_f32 v[84:85], v[84:85], v[108:109]
	v_mfma_f32_16x16x32_bf16 v[226:229], v[112:115], v[48:51], 0
	v_bfe_u32 v196, v216, 16, 1
	v_add3_u32 v196, v216, v196, s68
	v_bfe_u32 v195, v217, 16, 1
	v_mfma_f32_16x16x32_bf16 v[230:233], v[112:115], v[32:35], 0
	v_add3_u32 v195, v217, v195, s68
	v_mfma_f32_16x16x32_bf16 v[116:119], v[112:115], v[8:11], 0
	v_mfma_f32_16x16x32_bf16 v[124:127], v[112:115], v[24:27], 0
	v_mfma_f32_16x16x32_bf16 v[222:225], v[112:115], v[0:3], 0
	v_mfma_f32_16x16x32_bf16 v[132:135], v[112:115], v[4:7], 0
	v_mfma_f32_16x16x32_bf16 v[112:115], v[112:115], v[40:43], 0
	s_nop 5
	v_mov_b32_e32 v108, v223
	v_mov_b32_e32 v223, v224
	v_mov_b32_e32 v109, v225
	s_waitcnt lgkmcnt(0)
; #define LAS __attribute__((address_space(3)))
; #define MFMA16(a, b, c) __builtin_amdgcn_mfma_f32_16x16x32_bf16((a), (b), (c), 0, 0, 0)
; __device__ __forceinline__ unsigned pk2(float lo, float hi) { return f2bf(lo) | (f2bf(hi) << 16); }
; __device__ __forceinline__ float bflo(unsigned w) { return __uint_as_float(w << 16); }
; __device__ __forceinline__ float bfhi(unsigned w) { return __uint_as_float(w & 0xffff0000u); }
; __device__ __forceinline__ void sgu_item(LAS unsigned char* wl, const bf16* proj, bf16* ymix, const float* vstat, const float* sgu_g, const bf16* Wm, const float* sgu_b, int chunk, int h, int lane) {
;     ...
;             for (int ks = 0; ks < 4; ++ks) {
;                 LAS unsigned char* ad = wl + (ks * 32 + 8 * q + (r >> 2)) * VP2 + (16 * n) * 2 + 8 * (r & 3);
;                 const s16x4 lo = __builtin_bit_cast(s16x4, __builtin_amdgcn_ds_read_tr16_b64_v4i16((LAS s16x4*)ad));
;                 const s16x4 hi = __builtin_bit_cast(s16x4, __builtin_amdgcn_ds_read_tr16_b64_v4i16((LAS s16x4*)(ad + 4 * VP2)));
;                 const bf16x8 vf = __builtin_shufflevector(lo, hi, 0, 1, 2, 3, 4, 5, 6, 7);
; #pragma unroll
;                 for (int tb = 2 * ks; tb < 8; ++tb) z[tb] = MFMA16(vf, wmf[f++], z[tb]);
;             }
; #pragma unroll
;             for (int tb = 0; tb < 8; ++tb) { const v4u uu = uu8[tb]; const unsigned ux = n == 0 ? uu.x : uu.z, uy = n == 0 ? uu.y : uu.w;
;                 v2u o; o.x = pk2(bflo(ux) * (z[tb][0] + bias[tb]), bfhi(ux) * (z[tb][1] + bias[tb])); o.y = pk2(bflo(uy) * (z[tb][2] + bias[tb]), bfhi(uy) * (z[tb][3] + bias[tb]));
;                 if (n == 0) olo[tb] = o;
;                 else { v4u w; w.x = olo[tb].x; w.y = olo[tb].y; w.z = o.x; w.w = o.y; *(v4u*)(ymix + (R0 + 16 * tb + r) * D + 512 + colv + 8 * q) = w; } }
	v_mfma_f32_16x16x32_bf16 v[128:131], v[234:237], v[20:23], v[120:123]
	v_add_f32_e64 v222, v162, v222
	v_add_f32_e64 v223, v163, v223
	v_pk_add_f32 v[108:109], v[162:163], v[108:109]
	v_mfma_f32_16x16x32_bf16 v[120:123], v[234:237], v[56:59], v[226:229]
	v_mfma_f32_16x16x32_bf16 v[226:229], v[234:237], v[36:39], v[230:233]
	s_nop 2
	ds_read_b64_tr_b16 v[230:231], v220 offset:5152
	ds_read_b64_tr_b16 v[232:233], v220 offset:5472
	v_mfma_f32_16x16x32_bf16 v[136:139], v[234:237], v[12:15], v[116:119]
	v_mfma_f32_16x16x32_bf16 v[116:119], v[234:237], v[28:31], v[124:127]
	v_mfma_f32_16x16x32_bf16 v[112:115], v[234:237], v[44:47], v[112:115]
	s_waitcnt lgkmcnt(0)
	v_mfma_f32_16x16x32_bf16 v[124:127], v[230:233], v[52:55], v[116:119]
	v_mfma_f32_16x16x32_bf16 v[116:119], v[230:233], v[64:67], v[226:229]
	s_nop 2
	ds_read_b64_tr_b16 v[226:227], v220 offset:7712
	ds_read_b64_tr_b16 v[228:229], v220 offset:8032
	v_mfma_f32_16x16x32_bf16 v[112:115], v[230:233], v[72:75], v[112:115]
	s_waitcnt lgkmcnt(0)
	v_mfma_f32_16x16x32_bf16 v[116:119], v[226:229], v[68:71], v[116:119]
	v_mfma_f32_16x16x32_bf16 v[112:115], v[226:229], v[76:79], v[112:115]
	v_and_b32_e32 v227, 0xffff0000, v107
	v_and_b32_e32 v226, 0xffff0000, v106
	v_lshlrev_b32_e32 v107, 16, v107
	v_lshlrev_b32_e32 v106, 16, v106
	v_pk_mul_f32 v[106:107], v[222:223], v[106:107]
	v_pk_mul_f32 v[108:109], v[108:109], v[226:227]
	v_bfe_u32 v197, v106, 16, 1
	v_bfe_u32 v216, v107, 16, 1
	v_bfe_u32 v192, v109, 16, 1
	v_bfe_u32 v194, v108, 16, 1
	v_add3_u32 v107, v107, v216, s68
	v_add3_u32 v106, v106, v197, s68
	v_add3_u32 v108, v108, v194, s68
	v_add3_u32 v109, v109, v192, s68
	v_bfe_u32 v192, v214, 16, 1
	v_bfe_u32 v194, v215, 16, 1
	v_lshrrev_b32_e32 v106, 16, v106
	v_lshrrev_b32_e32 v107, 16, v107
	v_add3_u32 v194, v215, v194, s68
	v_add3_u32 v192, v214, v192, s68
	v_and_or_b32 v217, v109, s37, v107
	v_and_or_b32 v216, v108, s37, v106
	v_lshl_add_u64 v[106:107], v[182:183], 0, s[20:21]
	v_lshrrev_b32_e32 v192, 16, v192
	v_lshrrev_b32_e32 v194, 16, v194
	v_add_co_u32_e32 v108, vcc, s0, v106
	v_and_or_b32 v215, v195, s37, v194
	v_and_or_b32 v214, v196, s37, v192
	v_addc_co_u32_e32 v109, vcc, 0, v107, vcc
	global_store_dwordx4 v[108:109], v[214:217], off offset:1024
	v_mov_b32_e32 v108, v133
	v_mov_b32_e32 v109, v135
	v_mov_b32_e32 v133, v134
	v_pk_add_f32 v[108:109], v[164:165], v[108:109]
	v_and_b32_e32 v215, 0xffff0000, v103
	v_and_b32_e32 v214, 0xffff0000, v102
	v_pk_add_f32 v[132:133], v[164:165], v[132:133]
	v_lshlrev_b32_e32 v103, 16, v103
	v_lshlrev_b32_e32 v102, 16, v102
	v_pk_mul_f32 v[108:109], v[108:109], v[214:215]
	v_pk_mul_f32 v[102:103], v[132:133], v[102:103]
	v_bfe_u32 v134, v213, 16, 1
	v_bfe_u32 v132, v109, 16, 1
	v_bfe_u32 v133, v108, 16, 1
	v_bfe_u32 v135, v212, 16, 1
	v_add3_u32 v194, v213, v134, s68
	v_bfe_u32 v134, v102, 16, 1
	v_add3_u32 v192, v212, v135, s68
	v_add3_u32 v108, v108, v133, s68
	v_add3_u32 v109, v109, v132, s68
	v_bfe_u32 v132, v210, 16, 1
	v_bfe_u32 v133, v211, 16, 1
	v_bfe_u32 v135, v103, 16, 1
	v_add3_u32 v102, v102, v134, s68
	v_add3_u32 v103, v103, v135, s68
	v_add3_u32 v133, v211, v133, s68
	v_add3_u32 v132, v210, v132, s68
	v_lshrrev_b32_e32 v102, 16, v102
	s_mov_b32 s0, 0x10908000
	v_lshrrev_b32_e32 v132, 16, v132
	v_lshrrev_b32_e32 v133, 16, v133
	v_lshrrev_b32_e32 v103, 16, v103
	v_and_or_b32 v134, v108, s37, v102
	v_add_co_u32_e32 v102, vcc, s0, v106
	v_and_or_b32 v135, v109, s37, v103
	v_and_or_b32 v133, v194, s37, v133
	v_and_or_b32 v132, v192, s37, v132
	v_addc_co_u32_e32 v103, vcc, 0, v107, vcc
	global_store_dwordx4 v[102:103], v[132:135], off offset:1024
	v_mov_b32_e32 v102, v137
	v_mov_b32_e32 v103, v139
	v_pk_add_f32 v[102:103], v[166:167], v[102:103]
	v_and_b32_e32 v109, 0xffff0000, v99
	v_and_b32_e32 v108, 0xffff0000, v98
	v_mov_b32_e32 v137, v138
	v_pk_mul_f32 v[102:103], v[102:103], v[108:109]
	v_pk_add_f32 v[108:109], v[166:167], v[136:137]
	v_lshlrev_b32_e32 v99, 16, v99
	v_lshlrev_b32_e32 v98, 16, v98
	v_pk_mul_f32 v[98:99], v[108:109], v[98:99]
	v_bfe_u32 v133, v208, 16, 1
	v_bfe_u32 v108, v103, 16, 1
	v_bfe_u32 v109, v102, 16, 1
	v_add3_u32 v136, v208, v133, s68
	v_bfe_u32 v133, v98, 16, 1
	v_add3_u32 v102, v102, v109, s68
	v_add3_u32 v103, v103, v108, s68
	v_bfe_u32 v108, v206, 16, 1
	v_bfe_u32 v109, v207, 16, 1
	v_bfe_u32 v134, v99, 16, 1
	v_add3_u32 v98, v98, v133, s68
	v_bfe_u32 v132, v209, 16, 1
	v_add3_u32 v99, v99, v134, s68
	v_add3_u32 v109, v207, v109, s68
	v_add3_u32 v108, v206, v108, s68
	v_lshrrev_b32_e32 v98, 16, v98
	s_mov_b32 s0, 0x10910000
	v_add3_u32 v132, v209, v132, s68
	v_lshrrev_b32_e32 v108, 16, v108
	v_lshrrev_b32_e32 v109, 16, v109
	v_lshrrev_b32_e32 v99, 16, v99
	v_and_or_b32 v134, v102, s37, v98
	v_add_co_u32_e32 v98, vcc, s0, v106
	v_and_or_b32 v135, v103, s37, v99
	v_and_or_b32 v133, v132, s37, v109
	v_and_or_b32 v132, v136, s37, v108
	v_addc_co_u32_e32 v99, vcc, 0, v107, vcc
	global_store_dwordx4 v[98:99], v[132:135], off offset:1024
	v_mov_b32_e32 v98, v129
	v_mov_b32_e32 v99, v131
	v_pk_add_f32 v[98:99], v[168:169], v[98:99]
	v_and_b32_e32 v103, 0xffff0000, v95
	v_and_b32_e32 v102, 0xffff0000, v94
	v_mov_b32_e32 v129, v130
	v_pk_mul_f32 v[98:99], v[98:99], v[102:103]
	v_pk_add_f32 v[102:103], v[168:169], v[128:129]
	v_lshlrev_b32_e32 v95, 16, v95
	v_lshlrev_b32_e32 v94, 16, v94
	v_pk_mul_f32 v[94:95], v[102:103], v[94:95]
	v_bfe_u32 v102, v99, 16, 1
	v_bfe_u32 v103, v98, 16, 1
	v_add3_u32 v98, v98, v103, s68
	v_add3_u32 v99, v99, v102, s68
	v_bfe_u32 v102, v202, 16, 1
	v_bfe_u32 v103, v203, 16, 1
	v_bfe_u32 v128, v94, 16, 1
	v_bfe_u32 v129, v95, 16, 1
	v_bfe_u32 v108, v205, 16, 1
	v_bfe_u32 v109, v204, 16, 1
; __device__ __forceinline__ unsigned pk2(float lo, float hi) { return f2bf(lo) | (f2bf(hi) << 16); }
; __device__ __forceinline__ float bflo(unsigned w) { return __uint_as_float(w << 16); }
; __device__ __forceinline__ float bfhi(unsigned w) { return __uint_as_float(w & 0xffff0000u); }
; #define LDS_WAIT() asm volatile("s_waitcnt lgkmcnt(0)" ::: "memory")
; __device__ __forceinline__ void sgu_item(LAS unsigned char* wl, const bf16* proj, bf16* ymix, const float* vstat, const float* sgu_g, const bf16* Wm, const float* sgu_b, int chunk, int h, int lane) {
;     ...
;             for (int tb = 0; tb < 8; ++tb) { const v4u uu = uu8[tb]; const unsigned ux = n == 0 ? uu.x : uu.z, uy = n == 0 ? uu.y : uu.w;
;                 v2u o; o.x = pk2(bflo(ux) * (z[tb][0] + bias[tb]), bfhi(ux) * (z[tb][1] + bias[tb])); o.y = pk2(bflo(uy) * (z[tb][2] + bias[tb]), bfhi(uy) * (z[tb][3] + bias[tb]));
;                 if (n == 0) olo[tb] = o;
;                 else { v4u w; w.x = olo[tb].x; w.y = olo[tb].y; w.z = o.x; w.w = o.y; *(v4u*)(ymix + (R0 + 16 * tb + r) * D + 512 + colv + 8 * q) = w; } }
;         }
;         LDS_WAIT();
	v_add3_u32 v95, v95, v129, s68
	v_add3_u32 v94, v94, v128, s68
	v_add3_u32 v103, v203, v103, s68
	v_add3_u32 v102, v202, v102, s68
	v_add3_u32 v109, v204, v109, s68
	v_add3_u32 v108, v205, v108, s68
	v_lshrrev_b32_e32 v102, 16, v102
	v_lshrrev_b32_e32 v103, 16, v103
	v_lshrrev_b32_e32 v94, 16, v94
	v_lshrrev_b32_e32 v95, 16, v95
	v_and_or_b32 v131, v99, s37, v95
	v_and_or_b32 v130, v98, s37, v94
	v_and_or_b32 v129, v108, s37, v103
	v_and_or_b32 v128, v109, s37, v102
	v_lshl_add_u64 v[94:95], v[184:185], 0, s[20:21]
	global_store_dwordx4 v[94:95], v[128:131], off
	v_mov_b32_e32 v94, v125
	v_mov_b32_e32 v95, v127
	v_pk_add_f32 v[94:95], v[170:171], v[94:95]
	v_and_b32_e32 v99, 0xffff0000, v91
	v_and_b32_e32 v98, 0xffff0000, v90
	v_mov_b32_e32 v125, v126
	v_pk_mul_f32 v[94:95], v[94:95], v[98:99]
	v_pk_add_f32 v[98:99], v[170:171], v[124:125]
	v_lshlrev_b32_e32 v91, 16, v91
	v_lshlrev_b32_e32 v90, 16, v90
	v_pk_mul_f32 v[90:91], v[98:99], v[90:91]
	v_bfe_u32 v103, v200, 16, 1
	v_bfe_u32 v98, v95, 16, 1
	v_bfe_u32 v99, v94, 16, 1
	v_add3_u32 v108, v200, v103, s68
	v_bfe_u32 v103, v90, 16, 1
	v_mfma_f32_16x16x32_bf16 v[120:123], v[230:233], v[60:63], v[120:123]
	v_add3_u32 v94, v94, v99, s68
	v_add3_u32 v95, v95, v98, s68
	v_bfe_u32 v98, v104, 16, 1
	v_bfe_u32 v99, v105, 16, 1
	v_bfe_u32 v109, v91, 16, 1
	v_add3_u32 v90, v90, v103, s68
	v_bfe_u32 v102, v201, 16, 1
	v_add3_u32 v91, v91, v109, s68
	v_add3_u32 v99, v105, v99, s68
	v_add3_u32 v98, v104, v98, s68
	v_lshrrev_b32_e32 v90, 16, v90
	s_mov_b32 s0, 0x10920000
	v_add3_u32 v102, v201, v102, s68
	v_lshrrev_b32_e32 v98, 16, v98
	v_lshrrev_b32_e32 v99, 16, v99
	v_lshrrev_b32_e32 v91, 16, v91
	v_and_or_b32 v104, v94, s37, v90
	v_add_co_u32_e32 v90, vcc, s0, v106
	v_and_or_b32 v105, v95, s37, v91
	v_and_or_b32 v103, v102, s37, v99
	v_and_or_b32 v102, v108, s37, v98
	v_addc_co_u32_e32 v91, vcc, 0, v107, vcc
	global_store_dwordx4 v[90:91], v[102:105], off offset:1024
	v_mov_b32_e32 v90, v121
	v_mov_b32_e32 v91, v123
	v_pk_add_f32 v[90:91], v[172:173], v[90:91]
	v_and_b32_e32 v95, 0xffff0000, v87
	v_and_b32_e32 v94, 0xffff0000, v86
	v_mov_b32_e32 v121, v122
	v_pk_mul_f32 v[90:91], v[90:91], v[94:95]
	v_pk_add_f32 v[94:95], v[172:173], v[120:121]
	v_lshlrev_b32_e32 v87, 16, v87
	v_lshlrev_b32_e32 v86, 16, v86
	v_pk_mul_f32 v[86:87], v[94:95], v[86:87]
	v_bfe_u32 v99, v100, 16, 1
	v_bfe_u32 v94, v91, 16, 1
	v_bfe_u32 v95, v90, 16, 1
	v_bfe_u32 v98, v101, 16, 1
	v_add3_u32 v99, v100, v99, s68
	v_bfe_u32 v100, v86, 16, 1
	v_add3_u32 v98, v101, v98, s68
	v_add3_u32 v90, v90, v95, s68
	v_add3_u32 v91, v91, v94, s68
	v_bfe_u32 v94, v96, 16, 1
	v_bfe_u32 v95, v97, 16, 1
	v_bfe_u32 v101, v87, 16, 1
	v_add3_u32 v86, v86, v100, s68
	v_add3_u32 v87, v87, v101, s68
	v_add3_u32 v95, v97, v95, s68
	v_add3_u32 v94, v96, v94, s68
	v_lshrrev_b32_e32 v86, 16, v86
	s_mov_b32 s0, 0x10928000
	v_lshrrev_b32_e32 v94, 16, v94
	v_lshrrev_b32_e32 v95, 16, v95
	v_lshrrev_b32_e32 v87, 16, v87
	v_and_or_b32 v96, v90, s37, v86
	v_add_co_u32_e32 v86, vcc, s0, v106
	v_and_or_b32 v97, v91, s37, v87
	v_and_or_b32 v95, v98, s37, v95
	v_and_or_b32 v94, v99, s37, v94
	v_addc_co_u32_e32 v87, vcc, 0, v107, vcc
	global_store_dwordx4 v[86:87], v[94:97], off offset:1024
	v_mov_b32_e32 v86, v117
	v_mov_b32_e32 v87, v119
	v_pk_add_f32 v[86:87], v[174:175], v[86:87]
	v_and_b32_e32 v91, 0xffff0000, v83
	v_and_b32_e32 v90, 0xffff0000, v82
	v_mov_b32_e32 v117, v118
	v_pk_mul_f32 v[86:87], v[86:87], v[90:91]
	v_pk_add_f32 v[90:91], v[174:175], v[116:117]
	v_lshlrev_b32_e32 v83, 16, v83
	v_lshlrev_b32_e32 v82, 16, v82
	v_pk_mul_f32 v[82:83], v[90:91], v[82:83]
	v_bfe_u32 v94, v93, 16, 1
	v_bfe_u32 v90, v87, 16, 1
	v_bfe_u32 v91, v86, 16, 1
	v_bfe_u32 v95, v92, 16, 1
	v_add3_u32 v93, v93, v94, s68
	v_bfe_u32 v94, v82, 16, 1
	v_add3_u32 v92, v92, v95, s68
	v_add3_u32 v86, v86, v91, s68
	v_add3_u32 v87, v87, v90, s68
	v_bfe_u32 v90, v80, 16, 1
	v_bfe_u32 v91, v81, 16, 1
	v_bfe_u32 v95, v83, 16, 1
	v_add3_u32 v82, v82, v94, s68
	v_add3_u32 v83, v83, v95, s68
	v_add3_u32 v81, v81, v91, s68
	v_add3_u32 v80, v80, v90, s68
	v_lshrrev_b32_e32 v82, 16, v82
	s_mov_b32 s0, 0x10930000
	v_lshrrev_b32_e32 v80, 16, v80
	v_lshrrev_b32_e32 v81, 16, v81
	v_lshrrev_b32_e32 v83, 16, v83
	v_and_or_b32 v82, v86, s37, v82
	v_add_co_u32_e32 v86, vcc, s0, v106
	v_and_or_b32 v83, v87, s37, v83
	v_and_or_b32 v81, v93, s37, v81
	v_and_or_b32 v80, v92, s37, v80
	v_addc_co_u32_e32 v87, vcc, 0, v107, vcc
	global_store_dwordx4 v[86:87], v[80:83], off offset:1024
	v_lshlrev_b32_e32 v87, 16, v111
	v_lshlrev_b32_e32 v86, 16, v110
	v_mov_b32_e32 v80, v113
	v_mov_b32_e32 v81, v115
	v_pk_add_f32 v[80:81], v[176:177], v[80:81]
	v_and_b32_e32 v83, 0xffff0000, v111
	v_and_b32_e32 v82, 0xffff0000, v110
	v_mov_b32_e32 v113, v114
	v_pk_mul_f32 v[80:81], v[80:81], v[82:83]
	v_pk_add_f32 v[82:83], v[176:177], v[112:113]
	v_bfe_u32 v90, v89, 16, 1
	v_pk_mul_f32 v[82:83], v[82:83], v[86:87]
	v_bfe_u32 v86, v81, 16, 1
	v_bfe_u32 v87, v80, 16, 1
	v_bfe_u32 v91, v88, 16, 1
	v_add3_u32 v88, v88, v91, s68
	v_add3_u32 v89, v89, v90, s68
	v_add3_u32 v80, v80, v87, s68
	v_add3_u32 v81, v81, v86, s68
	v_bfe_u32 v86, v84, 16, 1
	v_bfe_u32 v87, v85, 16, 1
	v_bfe_u32 v90, v82, 16, 1
	v_bfe_u32 v91, v83, 16, 1
	v_add3_u32 v83, v83, v91, s68
	v_add3_u32 v82, v82, v90, s68
	v_add3_u32 v85, v85, v87, s68
	v_add3_u32 v84, v84, v86, s68
	v_lshrrev_b32_e32 v84, 16, v84
	v_lshrrev_b32_e32 v85, 16, v85
	v_lshrrev_b32_e32 v82, 16, v82
	v_lshrrev_b32_e32 v83, 16, v83
	v_and_or_b32 v83, v81, s37, v83
	v_and_or_b32 v82, v80, s37, v82
	v_and_or_b32 v81, v89, s37, v85
	v_and_or_b32 v80, v88, s37, v84
	v_lshl_add_u64 v[84:85], v[180:181], 0, s[20:21]
	global_store_dwordx4 v[84:85], v[80:83], off
	s_waitcnt lgkmcnt(0)
	s_add_u32 s20, s20, 64
	s_addc_u32 s21, s21, 0
	s_cmpk_lg_i32 s20, 0x100
	s_cbranch_scc1 .LBB0_511
	s_add_i32 s5, s5, s77
	s_add_i32 s4, s4, s7
	s_cmp_lt_i32 s5, s2
	s_cbranch_scc1 .LBB0_510
